# attention: prefetch next K tile into spare VGPRs during current tile (counted vmcnt), on top of v7
# baseline (speedup 1.0000x reference)
; DI void attn_phase(const Prm& p, LAS unsigned char* lds, int wave, int gw, int NGW, int lane) {
;     ...
;         const size_t tbase = (size_t)(b * 8 + h) * (smp ? 34 : 129) * 4096 + lane * 8;
;         const bf16_t* Kb = (smp ? p.KS : p.KP) + tbase; const bf16_t* Vb = (smp ? p.VTS : p.VTP) + tbase;
;         const int qpos0 = (smp ? 1024 : 0) + 32 * qb, qrow0 = smp ? NTP + b * 64 + 32 * qb : b * TP + 32 * qb;
;         const int qpos = qpos0 + q; const bool qvalid = smp || qpos < TP; const size_t qrow = qvalid ? qrow0 + q : qrow0;
;         bf16x8 qf[8];
; #pragma unroll
;         for (int ks = 0; ks < 8; ++ks) qf[ks] = *(const bf16x8*)(p.Q + qrow * 1024 + h * 128 + 16 * ks + 8 * half);
;         f32x16 o[4];
; #pragma unroll
;         for (int db = 0; db < 4; ++db)
; #pragma unroll
;             for (int e = 0; e < 16; ++e) o[db][e] = 0.f;
;         float C = 1.f;
;     ...
;             f32x16 s;
; #pragma unroll
;             for (int e = 0; e < 16; ++e) s[e] = 0.f;
;             const bf16_t* kr = Kb + (size_t)kt * 4096; const bf16_t* vr = Vb + (size_t)kt * 4096;
;             bf16x8 kf[8], vf[8];
; #pragma unroll
;             for (int ks = 0; ks < 8; ++ks) kf[ks] = *(const bf16x8*)(kr + ks * 512);
; #pragma unroll
;             for (int ks = 0; ks < 8; ++ks) vf[ks] = *(const bf16x8*)(vr + ks * 512);
; #pragma unroll
.LBB0_2112:
	s_and_b64 s[12:13], s[10:11], exec
	s_cselect_b32 s18, 0x400, 0
	s_lshl_b32 s8, s8, 5
	s_add_i32 s18, s18, s8
	s_lshl_b32 s12, s15, 7
	s_add_i32 s17, s17, s8
	s_ashr_i32 s13, s12, 31
	s_ashr_i32 s8, s18, 5
	s_cmp_lt_i32 s8, 0
	s_cbranch_scc1 .LBB0_2117
	v_or_b32_e32 v172, s18, v153
	v_cmp_gt_i32_e32 vcc, s3, v172
	s_or_b64 vcc, s[10:11], vcc
	v_readlane_b32 s40, v255, 8
	v_cndmask_b32_e32 v0, 0, v153, vcc
	v_add_u32_e32 v0, s17, v0
	v_ashrrev_i32_e32 v1, 31, v0
	v_lshlrev_b64 v[0:1], 11, v[0:1]
	v_readlane_b32 s54, v255, 22
	v_readlane_b32 s55, v255, 23
	s_lshl_b32 s14, s14, 3
	s_add_i32 s19, s14, s15
	v_lshl_add_u64 v[0:1], s[54:55], 0, v[0:1]
	v_lshl_add_u64 v[0:1], s[12:13], 1, v[0:1]
	v_lshl_add_u64 v[0:1], v[0:1], 0, v[144:145]
	global_load_dwordx4 v[80:83], v[0:1], off
	global_load_dwordx4 v[84:87], v[0:1], off offset:32
	global_load_dwordx4 v[88:91], v[0:1], off offset:64
	global_load_dwordx4 v[92:95], v[0:1], off offset:96
	global_load_dwordx4 v[96:99], v[0:1], off offset:128
	global_load_dwordx4 v[100:103], v[0:1], off offset:160
	global_load_dwordx4 v[104:107], v[0:1], off offset:192
	global_load_dwordx4 v[108:111], v[0:1], off offset:224
	s_and_b64 s[14:15], s[10:11], exec
	v_readlane_b32 s24, v254, 0
	v_readlane_b32 s25, v254, 1
	v_readlane_b32 s26, v254, 2
	v_readlane_b32 s27, v254, 3
	v_readlane_b32 s28, v254, 4
	v_readlane_b32 s29, v254, 5
	v_readlane_b32 s30, v254, 6
	v_readlane_b32 s31, v254, 7
	s_cselect_b32 s14, s4, 0x102000
	s_cselect_b32 s20, s27, s25
	s_cselect_b32 s21, s26, s24
	s_cselect_b32 s22, s31, s29
	s_cselect_b32 s23, s30, s28
	s_mul_hi_i32 s24, s14, s19
	s_mul_i32 s19, s14, s19
	s_lshl_b64 s[14:15], s[8:9], 13
	s_add_u32 s19, s19, s14
	s_addc_u32 s24, s24, s15
	s_add_u32 s14, s21, s19
	v_cmp_lt_i32_e32 vcc, v168, v169
	s_addc_u32 s15, s20, s24
	s_add_u32 s20, s23, s19
	v_cndmask_b32_e32 v0, v167, v168, vcc
	v_mov_b32_e32 v48, 0
	v_lshlrev_b32_e32 v173, 2, v0
	v_add_u32_e32 v174, s18, v165
	s_addc_u32 s21, s22, s24
	v_mov_b32_e32 v175, 1.0
	v_mov_b32_e32 v176, s8
	v_mov_b32_e32 v49, v48
	v_mov_b32_e32 v50, v48
	v_mov_b32_e32 v51, v48
	v_mov_b32_e32 v52, v48
	v_mov_b32_e32 v53, v48
	v_mov_b32_e32 v54, v48
	v_mov_b32_e32 v55, v48
	v_mov_b32_e32 v56, v48
	v_mov_b32_e32 v57, v48
	v_mov_b32_e32 v58, v48
	v_mov_b32_e32 v59, v48
	v_mov_b32_e32 v60, v48
	v_mov_b32_e32 v61, v48
	v_mov_b32_e32 v62, v48
	v_mov_b32_e32 v63, v48
	v_mov_b32_e32 v32, v48
	v_mov_b32_e32 v33, v48
	v_mov_b32_e32 v34, v48
	v_mov_b32_e32 v35, v48
	v_mov_b32_e32 v36, v48
	v_mov_b32_e32 v37, v48
	v_mov_b32_e32 v38, v48
	v_mov_b32_e32 v39, v48
	v_mov_b32_e32 v40, v48
	v_mov_b32_e32 v41, v48
	v_mov_b32_e32 v42, v48
	v_mov_b32_e32 v43, v48
	v_mov_b32_e32 v44, v48
	v_mov_b32_e32 v45, v48
	v_mov_b32_e32 v46, v48
	v_mov_b32_e32 v47, v48
	v_mov_b32_e32 v16, v48
	v_mov_b32_e32 v17, v48
	v_mov_b32_e32 v18, v48
	v_mov_b32_e32 v19, v48
	v_mov_b32_e32 v20, v48
	v_mov_b32_e32 v21, v48
	v_mov_b32_e32 v22, v48
	v_mov_b32_e32 v23, v48
	v_mov_b32_e32 v24, v48
	v_mov_b32_e32 v25, v48
	v_mov_b32_e32 v26, v48
	v_mov_b32_e32 v27, v48
	v_mov_b32_e32 v28, v48
	v_mov_b32_e32 v29, v48
	v_mov_b32_e32 v30, v48
	v_mov_b32_e32 v31, v48
	v_mov_b32_e32 v0, v48
	v_mov_b32_e32 v1, v48
	v_mov_b32_e32 v2, v48
	v_mov_b32_e32 v3, v48
	v_mov_b32_e32 v4, v48
	v_mov_b32_e32 v5, v48
	v_mov_b32_e32 v6, v48
	v_mov_b32_e32 v7, v48
	v_mov_b32_e32 v8, v48
	v_mov_b32_e32 v9, v48
	v_mov_b32_e32 v10, v48
	v_mov_b32_e32 v11, v48
	v_mov_b32_e32 v12, v48
	v_mov_b32_e32 v13, v48
	v_mov_b32_e32 v14, v48
	v_mov_b32_e32 v15, v48
	v_readlane_b32 s41, v255, 9
	v_readlane_b32 s42, v255, 10
	v_readlane_b32 s43, v255, 11
	v_readlane_b32 s44, v255, 12
	v_readlane_b32 s45, v255, 13
	v_readlane_b32 s46, v255, 14
	v_readlane_b32 s47, v255, 15
	v_readlane_b32 s48, v255, 16
	v_readlane_b32 s49, v255, 17
	v_readlane_b32 s50, v255, 18
	v_readlane_b32 s51, v255, 19
	v_readlane_b32 s52, v255, 20
	v_readlane_b32 s53, v255, 21
	s_mov_b32 s56, 0xffffe000
	s_mov_b32 s57, -1
	s_mov_b32 s58, 0x1000
	s_mov_b32 s59, 0
	v_lshl_add_u64 v[68:69], s[14:15], 0, v[148:149]
	global_load_dwordx4 v[64:67], v[68:69], off
	global_load_dwordx4 v[178:181], v[68:69], off offset:1024
	global_load_dwordx4 v[182:185], v[68:69], off offset:2048
	global_load_dwordx4 v[186:189], v[68:69], off offset:3072
	v_lshl_add_u64 v[68:69], v[68:69], 0, s[58:59]
	global_load_dwordx4 v[190:193], v[68:69], off
	global_load_dwordx4 v[194:197], v[68:69], off offset:1024
	global_load_dwordx4 v[198:201], v[68:69], off offset:2048
	global_load_dwordx4 v[202:205], v[68:69], off offset:3072
; #define MFMA32(a, b, c) __builtin_amdgcn_mfma_f32_32x32x16_bf16((a), (b), (c), 0, 0, 0)
; DI void attn_phase(const Prm& p, LAS unsigned char* lds, int wave, int gw, int NGW, int lane) {
;     ...
;             const bf16_t* kr = Kb + (size_t)kt * 4096; const bf16_t* vr = Vb + (size_t)kt * 4096;
;             bf16x8 kf[8], vf[8];
; #pragma unroll
;             for (int ks = 0; ks < 8; ++ks) kf[ks] = *(const bf16x8*)(kr + ks * 512);
; #pragma unroll
;             for (int ks = 0; ks < 8; ++ks) vf[ks] = *(const bf16x8*)(vr + ks * 512);
; #pragma unroll
;             for (int ks = 0; ks < 8; ++ks) s = MFMA32(kf[ks], qf[ks], s);
;             float pr[16], be[16], G[4], Gp[4];
; #pragma unroll
;             for (int i = 0; i < 4; ++i) {
; #pragma unroll
;                 for (int j = 0; j < 4; ++j) { const int key = 32 * kt + 8 * i + 4 * half + j; const bool valid = key < qpos;
;                     float z = s[4 * i + j] * 0.08838834764831845f; z = fminf(fmaxf(z, -80.f), 80.f);
;                     const float e = __expf(z), pp = __builtin_amdgcn_rcpf(1.f + e); pr[4 * i + j] = valid ? pp : 1.f; be[4 * i + j] = valid ? e * pp : 0.f; }
;                 G[i] = (pr[4 * i] * pr[4 * i + 1]) * (pr[4 * i + 2] * pr[4 * i + 3]); }
.LBB0_2114:
	v_lshl_add_u64 v[68:69], s[20:21], 0, v[148:149]
	global_load_dwordx4 v[140:143], v[68:69], off
	global_load_dwordx4 v[136:139], v[68:69], off offset:1024
	global_load_dwordx4 v[132:135], v[68:69], off offset:2048
	global_load_dwordx4 v[128:131], v[68:69], off offset:3072
	v_add_co_u32_e32 v68, vcc, s5, v68
	s_nop 1
	v_addc_co_u32_e32 v69, vcc, 0, v69, vcc
	global_load_dwordx4 v[124:127], v[68:69], off
	global_load_dwordx4 v[112:115], v[68:69], off offset:1024
	global_load_dwordx4 v[116:119], v[68:69], off offset:2048
	global_load_dwordx4 v[120:123], v[68:69], off offset:3072
	v_lshl_add_u64 v[238:239], s[14:15], 0, v[148:149]
	v_subrev_u32_e32 v150, 27, v174
	v_lshl_add_u64 v[238:239], v[238:239], 0, s[56:57]
	global_load_dwordx4 v[206:209], v[238:239], off
	global_load_dwordx4 v[210:213], v[238:239], off offset:1024
	global_load_dwordx4 v[214:217], v[238:239], off offset:2048
	global_load_dwordx4 v[218:221], v[238:239], off offset:3072
	v_lshl_add_u64 v[238:239], v[238:239], 0, s[58:59]
	global_load_dwordx4 v[222:225], v[238:239], off
	global_load_dwordx4 v[226:229], v[238:239], off offset:1024
	global_load_dwordx4 v[230:233], v[238:239], off offset:2048
	global_load_dwordx4 v[234:237], v[238:239], off offset:3072
	v_cmp_lt_i32_e32 vcc, v150, v172
	s_waitcnt vmcnt(16)
	v_mfma_f32_32x32x16_bf16 v[64:79], v[64:67], v[80:83], 0
	v_mfma_f32_32x32x16_bf16 v[64:79], v[178:181], v[84:87], v[64:79]
	v_mfma_f32_32x32x16_bf16 v[64:79], v[182:185], v[88:91], v[64:79]
	v_mfma_f32_32x32x16_bf16 v[64:79], v[186:189], v[92:95], v[64:79]
	v_mfma_f32_32x32x16_bf16 v[64:79], v[190:193], v[96:99], v[64:79]
	v_mfma_f32_32x32x16_bf16 v[64:79], v[194:197], v[100:103], v[64:79]
	v_mfma_f32_32x32x16_bf16 v[64:79], v[198:201], v[104:107], v[64:79]
	v_mfma_f32_32x32x16_bf16 v[64:79], v[202:205], v[108:111], v[64:79]
	s_nop 11
	v_mul_f32_e32 v64, 0x3db504f3, v64
	v_med3_f32 v64, v64, s6, v170
	v_mul_f32_e32 v64, 0x3fb8aa3b, v64
	v_exp_f32_e32 v150, v64
	v_mul_f32_e32 v65, 0x3db504f3, v65
	v_med3_f32 v65, v65, s6, v170
	v_mul_f32_e32 v65, 0x3fb8aa3b, v65
	v_add_f32_e32 v64, 1.0, v150
	v_rcp_f32_e32 v151, v64
	v_exp_f32_e32 v65, v65
	v_mul_f32_e32 v77, 0x3db504f3, v77
	v_med3_f32 v77, v77, s6, v170
	v_mul_f32_e32 v150, v150, v151
	v_cndmask_b32_e32 v177, 0, v150, vcc
	v_subrev_u32_e32 v150, 26, v174
	v_cndmask_b32_e32 v64, 1.0, v151, vcc
	v_cmp_lt_i32_e32 vcc, v150, v172
	v_add_f32_e32 v150, 1.0, v65
	v_rcp_f32_e32 v151, v150
	v_mul_f32_e32 v77, 0x3fb8aa3b, v77
	v_mul_f32_e32 v78, 0x3db504f3, v78
	v_med3_f32 v78, v78, s6, v170
	v_mul_f32_e32 v65, v65, v151
	v_cndmask_b32_e32 v178, 0, v65, vcc
	v_subrev_u32_e32 v65, 25, v174
	v_cndmask_b32_e32 v150, 1.0, v151, vcc
	v_cmp_lt_i32_e32 vcc, v65, v172
	v_mul_f32_e32 v65, 0x3db504f3, v66
	v_med3_f32 v65, v65, s6, v170
	v_mul_f32_e32 v65, 0x3fb8aa3b, v65
	v_exp_f32_e32 v65, v65
	v_mul_f32_e32 v78, 0x3fb8aa3b, v78
	v_mul_f32_e32 v79, 0x3db504f3, v79
	v_med3_f32 v79, v79, s6, v170
	v_add_f32_e32 v66, 1.0, v65
	v_rcp_f32_e32 v151, v66
	v_mul_f32_e32 v79, 0x3fb8aa3b, v79
	v_exp_f32_e32 v79, v79
	v_mul_f32_e32 v65, v65, v151
	v_cndmask_b32_e32 v179, 0, v65, vcc
	v_subrev_u32_e32 v65, 24, v174
	v_cndmask_b32_e32 v66, 1.0, v151, vcc
	v_cmp_lt_i32_e32 vcc, v65, v172
	v_mul_f32_e32 v65, 0x3db504f3, v67
	v_med3_f32 v65, v65, s6, v170
	v_mul_f32_e32 v65, 0x3fb8aa3b, v65
	v_exp_f32_e32 v65, v65
	s_nop 0
	v_add_f32_e32 v67, 1.0, v65
	v_rcp_f32_e32 v67, v67
	s_nop 0
	v_mul_f32_e32 v65, v65, v67
	v_cndmask_b32_e32 v180, 0, v65, vcc
	v_subrev_u32_e32 v65, 19, v174
	v_cndmask_b32_e32 v158, 1.0, v67, vcc
	v_cmp_lt_i32_e32 vcc, v65, v172
	v_mul_f32_e32 v65, 0x3db504f3, v68
	v_med3_f32 v65, v65, s6, v170
	v_mul_f32_e32 v65, 0x3fb8aa3b, v65
	v_exp_f32_e32 v65, v65
	s_nop 0
	v_add_f32_e32 v67, 1.0, v65
	v_rcp_f32_e32 v67, v67
	s_nop 0
	v_mul_f32_e32 v65, v65, v67
	v_cndmask_b32_e32 v68, 0, v65, vcc
	v_subrev_u32_e32 v65, 18, v174
	v_cndmask_b32_e32 v151, 1.0, v67, vcc
	v_cmp_lt_i32_e32 vcc, v65, v172
	v_mul_f32_e32 v65, 0x3db504f3, v69
	v_med3_f32 v65, v65, s6, v170
	v_mul_f32_e32 v65, 0x3fb8aa3b, v65
	v_exp_f32_e32 v65, v65
	s_nop 0
	v_add_f32_e32 v67, 1.0, v65
	v_rcp_f32_e32 v67, v67
	s_nop 0
	v_mul_f32_e32 v65, v65, v67
	v_cndmask_b32_e32 v181, 0, v65, vcc
	v_subrev_u32_e32 v65, 17, v174
	v_cndmask_b32_e32 v69, 1.0, v67, vcc
	v_cmp_lt_i32_e32 vcc, v65, v172
	v_mul_f32_e32 v65, 0x3db504f3, v70
	v_med3_f32 v65, v65, s6, v170
	v_mul_f32_e32 v65, 0x3fb8aa3b, v65
	v_exp_f32_e32 v65, v65
	s_nop 0
	v_add_f32_e32 v67, 1.0, v65
	v_rcp_f32_e32 v67, v67
	s_nop 0
	v_mul_f32_e32 v65, v65, v67
	v_cndmask_b32_e32 v182, 0, v65, vcc
	v_add_u32_e32 v65, -16, v174
	v_cndmask_b32_e32 v70, 1.0, v67, vcc
	v_cmp_lt_i32_e32 vcc, v65, v172
	v_mul_f32_e32 v65, 0x3db504f3, v71
	v_med3_f32 v65, v65, s6, v170
	v_mul_f32_e32 v65, 0x3fb8aa3b, v65
	v_exp_f32_e32 v65, v65
	s_nop 0
	v_add_f32_e32 v67, 1.0, v65
	v_rcp_f32_e32 v67, v67
	s_nop 0
	v_cndmask_b32_e32 v71, 1.0, v67, vcc
	v_mul_f32_e32 v65, v65, v67
	v_cndmask_b32_e32 v183, 0, v65, vcc
	v_mul_f32_e32 v65, v151, v69
	v_mul_f32_e32 v67, v70, v71
	v_mul_f32_e32 v65, v65, v67
	v_add_u32_e32 v67, -11, v174
	v_cmp_lt_i32_e32 vcc, v67, v172
	v_mul_f32_e32 v67, 0x3db504f3, v72
	v_med3_f32 v67, v67, s6, v170
	v_mul_f32_e32 v67, 0x3fb8aa3b, v67
	v_exp_f32_e32 v67, v67
	s_nop 0
	v_add_f32_e32 v72, 1.0, v67
	v_rcp_f32_e32 v72, v72
	s_nop 0
	v_mul_f32_e32 v67, v67, v72
	v_cndmask_b32_e32 v151, 1.0, v72, vcc
	v_cndmask_b32_e32 v72, 0, v67, vcc
	v_add_u32_e32 v67, -10, v174
	v_cmp_lt_i32_e32 vcc, v67, v172
	v_mul_f32_e32 v67, 0x3db504f3, v73
	v_med3_f32 v67, v67, s6, v170
	v_mul_f32_e32 v67, 0x3fb8aa3b, v67
; DI unsigned pk2(float lo, float hi) { unsigned r; asm volatile("v_cvt_pk_bf16_f32 %0, %1, %2" : "=v"(r) : "v"(lo), "v"(hi)); return r; }
; #define MFMA32(a, b, c) __builtin_amdgcn_mfma_f32_32x32x16_bf16((a), (b), (c), 0, 0, 0)
; DI void attn_phase(const Prm& p, LAS unsigned char* lds, int wave, int gw, int NGW, int lane) {
;     ...
;                 G[i] = (pr[4 * i] * pr[4 * i + 1]) * (pr[4 * i + 2] * pr[4 * i + 3]); }
; #pragma unroll
;             for (int i = 0; i < 4; ++i) Gp[i] = __shfl_xor(G[i], 32);
;             float w[16]; float E1 = 1.f;
; #pragma unroll
;             for (int i = 3; i >= 0; --i) { const float Glo = half ? Gp[i] : G[i], Ghi = half ? G[i] : Gp[i];
;                 float suf = C * (half ? E1 : E1 * Ghi);
; #pragma unroll
;                 for (int j = 3; j >= 0; --j) { w[4 * i + j] = be[4 * i + j] * suf; suf *= pr[4 * i + j]; }
;                 E1 *= Glo * Ghi; }
;             C *= E1;
; #pragma unroll
;             for (int c = 0; c < 2; ++c) { union { bf16x8 v; unsigned u[4]; } wf;
; #pragma unroll
;                 for (int e = 0; e < 4; ++e) wf.u[e] = pk2(w[8 * c + 2 * e], w[8 * c + 2 * e + 1]);
; #pragma unroll
;                 for (int db = 0; db < 4; ++db) o[db] = MFMA32(vf[4 * c + db], wf.v, o[db]); }
;             if (__all(C < 1e-24f)) break;
	v_exp_f32_e32 v67, v67
	s_nop 0
	v_add_f32_e32 v73, 1.0, v67
	v_rcp_f32_e32 v159, v73
	s_nop 0
	v_mul_f32_e32 v67, v67, v159
	v_cndmask_b32_e32 v73, 1.0, v159, vcc
	v_cndmask_b32_e32 v159, 0, v67, vcc
	v_add_u32_e32 v67, -9, v174
	v_cmp_lt_i32_e32 vcc, v67, v172
	v_mul_f32_e32 v67, 0x3db504f3, v74
	v_med3_f32 v67, v67, s6, v170
	v_mul_f32_e32 v67, 0x3fb8aa3b, v67
	v_exp_f32_e32 v67, v67
	s_nop 0
	v_add_f32_e32 v74, 1.0, v67
	v_rcp_f32_e32 v184, v74
	s_nop 0
	v_mul_f32_e32 v67, v67, v184
	v_cndmask_b32_e32 v74, 1.0, v184, vcc
	v_cndmask_b32_e32 v184, 0, v67, vcc
	v_add_u32_e32 v67, -8, v174
	v_cmp_lt_i32_e32 vcc, v67, v172
	v_mul_f32_e32 v67, 0x3db504f3, v75
	v_med3_f32 v67, v67, s6, v170
	v_mul_f32_e32 v67, 0x3fb8aa3b, v67
	v_exp_f32_e32 v67, v67
	s_nop 0
	v_add_f32_e32 v75, 1.0, v67
	v_rcp_f32_e32 v75, v75
	s_nop 0
	v_cndmask_b32_e32 v185, 1.0, v75, vcc
	v_mul_f32_e32 v67, v67, v75
	v_cndmask_b32_e32 v186, 0, v67, vcc
	v_mul_f32_e32 v67, v151, v73
	v_mul_f32_e32 v75, v74, v185
	v_mul_f32_e32 v75, v67, v75
	v_add_u32_e32 v67, -3, v174
	v_cmp_lt_i32_e32 vcc, v67, v172
	v_mul_f32_e32 v67, 0x3db504f3, v76
	v_med3_f32 v67, v67, s6, v170
	v_mul_f32_e32 v67, 0x3fb8aa3b, v67
	v_exp_f32_e32 v67, v67
	ds_bpermute_b32 v190, v173, v75
	v_add_f32_e32 v76, 1.0, v67
	v_rcp_f32_e32 v151, v76
	s_nop 0
	v_cndmask_b32_e32 v76, 1.0, v151, vcc
	v_mul_f32_e32 v67, v67, v151
	v_add_u32_e32 v151, -2, v174
	v_cndmask_b32_e32 v67, 0, v67, vcc
	v_cmp_lt_i32_e32 vcc, v151, v172
	v_exp_f32_e32 v151, v77
	s_nop 0
	v_add_f32_e32 v77, 1.0, v151
	v_rcp_f32_e32 v187, v77
	s_nop 0
	v_mul_f32_e32 v151, v151, v187
	v_cndmask_b32_e32 v77, 1.0, v187, vcc
	v_cndmask_b32_e32 v187, 0, v151, vcc
	v_add_u32_e32 v151, -1, v174
	v_cmp_lt_i32_e32 vcc, v151, v172
	v_exp_f32_e32 v151, v78
	v_mul_f32_e32 v76, v76, v77
	v_add_f32_e32 v78, 1.0, v151
	v_rcp_f32_e32 v188, v78
	s_nop 0
	v_mul_f32_e32 v151, v151, v188
	v_cndmask_b32_e32 v78, 1.0, v188, vcc
	v_cndmask_b32_e32 v188, 0, v151, vcc
	v_add_f32_e32 v151, 1.0, v79
	v_rcp_f32_e32 v151, v151
	v_cmp_lt_i32_e32 vcc, v174, v172
	v_subrev_u32_e32 v174, 32, v174
	v_mul_f32_e32 v79, v79, v151
	v_cndmask_b32_e32 v189, 1.0, v151, vcc
	v_mul_f32_e32 v151, v78, v189
	v_mul_f32_e32 v76, v76, v151
	ds_bpermute_b32 v191, v173, v76
	ds_bpermute_b32 v151, v173, v65
	v_cndmask_b32_e32 v79, 0, v79, vcc
	s_waitcnt lgkmcnt(1)
	v_cndmask_b32_e64 v192, 1.0, v191, s[0:1]
	v_mul_f32_e32 v192, v175, v192
	v_mul_f32_e32 v189, v192, v189
	v_mul_f32_e32 v78, v78, v189
	v_mul_f32_e32 v77, v77, v78
	v_mul_f32_e32 v77, v67, v77
	v_mul_f32_e32 v67, v76, v191
	v_mul_f32_e32 v76, v67, v190
	v_cndmask_b32_e64 v76, v67, v76, s[0:1]
	v_mul_f32_e32 v76, v175, v76
	v_mul_f32_e32 v187, v187, v78
	v_mul_f32_e32 v78, v186, v76
	v_mul_f32_e32 v76, v185, v76
	v_mul_f32_e32 v74, v74, v76
	v_mul_f32_e32 v184, v184, v76
	v_mul_f32_e32 v76, v159, v74
	v_mul_f32_e32 v73, v73, v74
	v_mul_f32_e32 v159, v75, v190
	v_mul_f32_e32 v74, v72, v73
	v_pk_mul_f32 v[72:73], v[66:67], v[158:159]
	s_waitcnt lgkmcnt(0)
	v_pk_mul_f32 v[64:65], v[64:65], v[150:151]
	v_mul_f32_e32 v79, v192, v79
	v_pk_mul_f32 v[64:65], v[64:65], v[72:73]
	v_mul_f32_e32 v72, v73, v151
	ds_bpermute_b32 v67, v173, v64
	v_cndmask_b32_e64 v72, v73, v72, s[0:1]
	v_mul_f32_e32 v72, v175, v72
	v_mul_f32_e32 v71, v71, v72
	v_mul_f32_e32 v70, v70, v71
	v_mul_f32_e32 v69, v69, v70
	v_mul_f32_e32 v68, v68, v69
	s_waitcnt lgkmcnt(0)
	v_mul_f32_e32 v69, v65, v67
	v_cndmask_b32_e64 v69, v65, v69, s[0:1]
	v_mul_f32_e32 v69, v175, v69
	v_mul_f32_e32 v73, v183, v72
	v_mul_f32_e32 v72, v182, v71
	v_mul_f32_e32 v71, v181, v70
	v_mul_f32_e32 v70, v180, v69
	v_mul_f32_e32 v69, v158, v69
	v_mul_f32_e32 v66, v66, v69
	v_mul_f32_e32 v75, v179, v69
	v_mul_f32_e32 v69, v178, v66
	v_mul_f32_e32 v66, v150, v66
	v_mul_f32_e32 v66, v177, v66
	v_mul_f32_e32 v64, v64, v67
	v_mul_f32_e32 v150, v64, v65
	v_cvt_pk_bf16_f32 v64, v66, v69
	v_cvt_pk_bf16_f32 v65, v75, v70
	v_cvt_pk_bf16_f32 v66, v68, v71
	v_cvt_pk_bf16_f32 v67, v72, v73
	v_mul_f32_e32 v175, v175, v150
	s_waitcnt vmcnt(15)
	v_mfma_f32_32x32x16_bf16 v[48:63], v[140:143], v[64:67], v[48:63]
	v_mul_f32_e32 v188, v189, v188
	v_cmp_gt_f32_e32 vcc, s7, v175
	s_cmp_lg_u64 vcc, exec
	s_cselect_b64 s[22:23], -1, 0
	v_add_co_u32_e32 v176, vcc, -1, v176
	s_and_b64 s[22:23], vcc, s[22:23]
	s_waitcnt vmcnt(14)
	v_mfma_f32_32x32x16_bf16 v[32:47], v[136:139], v[64:67], v[32:47]
	s_add_u32 s14, s14, 0xffffe000
	s_addc_u32 s15, s15, -1
	s_add_u32 s20, s20, 0xffffe000
	s_addc_u32 s21, s21, -1
	s_and_b64 vcc, exec, s[22:23]
	s_waitcnt vmcnt(13)
	v_mfma_f32_32x32x16_bf16 v[16:31], v[132:135], v[64:67], v[16:31]
	s_waitcnt vmcnt(12)
	v_mfma_f32_32x32x16_bf16 v[0:15], v[128:131], v[64:67], v[0:15]
	v_cvt_pk_bf16_f32 v64, v74, v76
	v_cvt_pk_bf16_f32 v65, v184, v78
	v_cvt_pk_bf16_f32 v66, v77, v187
	v_cvt_pk_bf16_f32 v67, v188, v79
	s_waitcnt vmcnt(11)
	v_mfma_f32_32x32x16_bf16 v[48:63], v[124:127], v[64:67], v[48:63]
	s_waitcnt vmcnt(10)
	v_mfma_f32_32x32x16_bf16 v[32:47], v[112:115], v[64:67], v[32:47]
	s_waitcnt vmcnt(9)
	v_mfma_f32_32x32x16_bf16 v[16:31], v[116:119], v[64:67], v[16:31]
	s_waitcnt vmcnt(8)
	v_mfma_f32_32x32x16_bf16 v[0:15], v[120:123], v[64:67], v[0:15]
	s_waitcnt vmcnt(0)
	v_mov_b64_e32 v[64:65], v[206:207]
	v_mov_b64_e32 v[66:67], v[208:209]
	v_mov_b64_e32 v[178:179], v[210:211]
	v_mov_b64_e32 v[180:181], v[212:213]
	v_mov_b64_e32 v[182:183], v[214:215]
	v_mov_b64_e32 v[184:185], v[216:217]
	v_mov_b64_e32 v[186:187], v[218:219]
	v_mov_b64_e32 v[188:189], v[220:221]
	v_mov_b64_e32 v[190:191], v[222:223]
	v_mov_b64_e32 v[192:193], v[224:225]
	v_mov_b64_e32 v[194:195], v[226:227]
	v_mov_b64_e32 v[196:197], v[228:229]
	v_mov_b64_e32 v[198:199], v[230:231]
	v_mov_b64_e32 v[200:201], v[232:233]
	v_mov_b64_e32 v[202:203], v[234:235]
	v_mov_b64_e32 v[204:205], v[236:237]
	s_cbranch_vccnz .LBB0_2114
	s_branch .LBB0_2118
